# first barrier: split arrive/poll lines (cg sync removed); rwkv in-proj: mu staged in LDS per tile
# speedup vs baseline: 1.1134x; 1.0059x over previous
.Lxb_nozero:
	buffer_wbl2 sc1
	s_waitcnt vmcnt(0)
	v_mov_b32_e32 v0, 0x3e280800
	v_mov_b32_e32 v1, 1
	global_atomic_add v1, v0, v1, s[94:95] sc0
	s_waitcnt vmcnt(0)
	v_readfirstlane_b32 s99, v1
	s_sub_u32 s100, s96, 1
	v_mov_b32_e32 v0, 0x3e280880
	s_cmp_lg_u32 s99, s100
	s_cbranch_scc1 .Lxb_first_poll
	v_mov_b32_e32 v1, 1
	global_atomic_add v0, v1, s[94:95]
.Lxb_first_poll:
	global_load_dword v1, v0, s[94:95] sc1
	s_waitcnt vmcnt(0)
	v_cmp_le_u32_e32 vcc, 1, v1
	s_cbranch_vccnz .LBB0_121
	s_sleep 1
	s_branch .Lxb_first_poll
.LBB0_121:
	buffer_inv sc1
	s_waitcnt vmcnt(0)
.LBB0_122:
	s_or_b64 exec, exec, s[0:1]
	s_add_u32 s0, s94, 0x8100000
	s_addc_u32 s1, s95, 0
	s_add_u32 s20, s94, 0xc180000
	s_addc_u32 s21, s95, 0
	s_add_u32 s6, s94, 0x28500000
	s_addc_u32 s7, s95, 0
	s_lshr_b32 s2, s88, 6
	s_and_b32 s3, s88, 7
	v_writelane_b32 v252, s2, 26
	s_and_b32 s2, s2, 0x3fffff8
	s_lshr_b32 s33, s96, 3
	s_or_b32 s2, s2, s3
	v_writelane_b32 v252, s3, 27
	s_cmpk_gt_u32 s2, 0xed
	v_lshrrev_b32_e32 v157, 3, v156
	v_and_b32_e32 v166, 56, v168
	v_lshrrev_b32_e32 v169, 1, v156
	v_and_b32_e32 v167, 64, v156
	v_and_b32_e32 v204, 31, v156
	s_barrier
	v_writelane_b32 v252, s2, 28
	s_cbranch_scc1 .LBB0_264
	v_mul_u32_u24_e32 v0, 0x48, v157
	s_movk_i32 s3, 0x1c0
	v_and_or_b32 v1, v169, s3, v164
	v_lshlrev_b32_e32 v64, 1, v166
	v_lshlrev_b32_e32 v0, 1, v0
	v_and_b32_e32 v2, 0x5f, v156
	v_mul_u32_u24_e32 v3, 0x48, v1
	v_add3_u32 v87, 0, v64, v0
	v_and_b32_e32 v0, 16, v169
	v_mul_u32_u24_e32 v2, 0x48, v2
	v_add_u32_e32 v5, 0, v0
	v_lshlrev_b32_e32 v3, 1, v3
	v_and_or_b32 v4, v157, 4, v167
	v_add_u32_e32 v88, v5, v3
	v_lshlrev_b32_e32 v2, 1, v2
	v_add_u32_e32 v3, 0, v3
	v_add_u32_e32 v90, v3, v0
	v_add3_u32 v91, 0, v2, v0
	v_mul_u32_u24_e32 v0, 0x180, v1
	v_lshlrev_b32_e32 v1, 2, v4
	v_add3_u32 v93, v3, v0, v1
	v_add_u32_e32 v0, 0x300, v156
	v_lshrrev_b32_e32 v94, 5, v0
	v_mul_u32_u24_e32 v0, 0x210, v94
	v_lshlrev_b32_e32 v1, 4, v204
	v_add3_u32 v95, v0, v1, 0
	v_add_u32_e32 v0, 0x200, v156
	v_lshrrev_b32_e32 v96, 5, v0
	v_mul_u32_u24_e32 v0, 0x210, v96
	v_add3_u32 v97, v0, v1, 0
	v_add_u32_e32 v0, 0x100, v156
	v_lshrrev_b32_e32 v98, 5, v0
	v_mul_u32_u24_e32 v0, 0x210, v98
	s_add_u32 s16, s94, 0x3e280000
	v_mov_b32_e32 v65, 0
	v_add3_u32 v99, v0, v1, 0
	v_mul_u32_u24_e32 v0, 0x210, v165
	s_addc_u32 s17, s95, 0
	s_lshr_b32 s2, s88, 3
	v_and_b32_e32 v86, 0x7c, v162
	v_lshl_add_u64 v[66:67], s[10:11], 0, v[64:65]
	v_lshl_add_u64 v[68:69], s[94:95], 0, v[64:65]
	v_add_u32_e32 v89, v5, v2
	v_add_u32_e32 v92, 0xd800, v87
	v_add3_u32 v100, v0, v1, 0
	v_readlane_b32 s3, v252, 28
	s_branch .LBB0_125

.LBB0_757:
	s_or_b64 exec, exec, s[24:25]
	s_lshr_b32 s24, s28, 3
	s_sub_i32 s25, s28, 21
	s_cmp_lt_i32 s28, 24
	s_cselect_b32 s24, s24, s25
	s_lshl_b32 s58, s24, 10
	v_lshlrev_b64 v[8:9], 11, v[8:9]
	s_mov_b64 s[24:25], 0x30000
	v_lshl_add_u64 v[8:9], v[8:9], 0, s[24:25]
	v_lshl_add_u64 v[18:19], v[126:127], 0, v[8:9]
	global_load_dwordx4 v[112:115], v[18:19], off
	v_add_u32_e32 v3, 0xffff0000, v2
	v_lshrrev_b32_e32 v20, 5, v3
	v_add_u32_e32 v3, 0xffff0020, v2
	v_add_u32_e32 v18, -1, v2
	v_cmp_lt_i32_e32 vcc, s70, v2
	v_add_u32_e32 v22, 31, v2
	v_cmp_lt_i32_e64 s[24:25], s71, v2
	v_lshrrev_b32_e32 v24, 5, v3
	v_add_u32_e32 v26, 63, v2
	v_cmp_lt_i32_e64 s[26:27], s72, v2
	v_add_u32_e32 v3, 0xffff0040, v2
	v_add_u32_e32 v30, 0x5f, v2
	v_cmp_lt_i32_e64 s[28:29], s73, v2
	v_add_u32_e32 v2, 0xffff0060, v2
	v_ashrrev_i32_e32 v19, 31, v18
	v_mov_b32_e32 v21, v64
	v_ashrrev_i32_e32 v23, 31, v22
	v_mov_b32_e32 v25, v64
	v_ashrrev_i32_e32 v27, 31, v26
	v_lshrrev_b32_e32 v28, 5, v3
	v_mov_b32_e32 v29, v64
	v_ashrrev_i32_e32 v31, 31, v30
	v_lshrrev_b32_e32 v2, 5, v2
	v_mov_b32_e32 v3, v64
	s_ashr_i32 s59, s58, 31
	v_lshlrev_b64 v[18:19], 11, v[18:19]
	v_lshlrev_b64 v[20:21], 12, v[20:21]
	v_lshlrev_b64 v[22:23], 11, v[22:23]
	v_lshlrev_b64 v[24:25], 12, v[24:25]
	v_lshlrev_b64 v[26:27], 11, v[26:27]
	v_lshlrev_b64 v[28:29], 12, v[28:29]
	v_lshlrev_b64 v[30:31], 11, v[30:31]
	v_lshlrev_b64 v[2:3], 12, v[2:3]
	v_lshl_add_u64 v[142:143], s[56:57], 0, v[0:1]
	v_mov_b32_e32 v0, 0
	v_lshl_add_u64 v[134:135], s[4:5], 0, v[4:5]
	v_lshl_add_u64 v[136:137], s[4:5], 0, v[10:11]
	v_lshl_add_u64 v[138:139], s[4:5], 0, v[16:17]
	v_lshl_add_u64 v[140:141], s[4:5], 0, v[8:9]
	v_lshl_add_u64 v[144:145], s[56:57], 0, v[18:19]
	v_lshl_add_u64 v[146:147], s[56:57], 0, v[6:7]
	v_lshl_add_u64 v[148:149], s[56:57], 0, v[22:23]
	v_lshl_add_u64 v[150:151], s[56:57], 0, v[12:13]
	v_lshl_add_u64 v[188:189], s[56:57], 0, v[26:27]
	v_lshl_add_u64 v[190:191], s[56:57], 0, v[14:15]
	v_lshl_add_u64 v[192:193], s[56:57], 0, v[30:31]
	v_lshl_add_u64 v[194:195], v[130:131], 0, v[20:21]
	v_lshl_add_u64 v[196:197], v[130:131], 0, v[24:25]
	v_lshl_add_u64 v[198:199], v[130:131], 0, v[28:29]
	v_lshl_add_u64 v[200:201], v[130:131], 0, v[2:3]
	v_lshl_add_u64 v[202:203], s[58:59], 2, v[132:133]
	s_mov_b64 s[58:59], 0
	v_mov_b32_e32 v1, v0
	v_mov_b32_e32 v2, v0
	v_mov_b32_e32 v3, v0
	v_mov_b32_e32 v4, v0
	v_mov_b32_e32 v5, v0
	v_mov_b32_e32 v6, v0
	v_mov_b32_e32 v7, v0
	v_mov_b32_e32 v8, v0
	v_mov_b32_e32 v9, v0
	v_mov_b32_e32 v10, v0
	v_mov_b32_e32 v11, v0
	v_mov_b32_e32 v12, v0
	v_mov_b32_e32 v13, v0
	v_mov_b32_e32 v14, v0
	v_mov_b32_e32 v15, v0
	v_mov_b32_e32 v48, v0
	v_mov_b32_e32 v49, v0
	v_mov_b32_e32 v50, v0
	v_mov_b32_e32 v51, v0
	v_mov_b32_e32 v52, v0
	v_mov_b32_e32 v53, v0
	v_mov_b32_e32 v54, v0
	v_mov_b32_e32 v55, v0
	v_mov_b32_e32 v56, v0
	v_mov_b32_e32 v57, v0
	v_mov_b32_e32 v58, v0
	v_mov_b32_e32 v59, v0
	v_mov_b32_e32 v60, v0
	v_mov_b32_e32 v61, v0
	v_mov_b32_e32 v62, v0
	v_mov_b32_e32 v63, v0
	v_mov_b32_e32 v32, v0
	v_mov_b32_e32 v33, v0
	v_mov_b32_e32 v34, v0
	v_mov_b32_e32 v35, v0
	v_mov_b32_e32 v36, v0
	v_mov_b32_e32 v37, v0
	v_mov_b32_e32 v38, v0
	v_mov_b32_e32 v39, v0
	v_mov_b32_e32 v40, v0
	v_mov_b32_e32 v41, v0
	v_mov_b32_e32 v42, v0
	v_mov_b32_e32 v43, v0
	v_mov_b32_e32 v44, v0
	v_mov_b32_e32 v45, v0
	v_mov_b32_e32 v46, v0
	v_mov_b32_e32 v47, v0
	v_mov_b32_e32 v16, v0
	v_mov_b32_e32 v17, v0
	v_mov_b32_e32 v18, v0
	v_mov_b32_e32 v19, v0
	v_mov_b32_e32 v20, v0
	v_mov_b32_e32 v21, v0
	v_mov_b32_e32 v22, v0
	v_mov_b32_e32 v23, v0
	v_mov_b32_e32 v24, v0
	v_mov_b32_e32 v25, v0
	v_mov_b32_e32 v26, v0
	v_mov_b32_e32 v27, v0
	v_mov_b32_e32 v28, v0
	v_mov_b32_e32 v29, v0
	v_mov_b32_e32 v30, v0
	v_mov_b32_e32 v31, v0
	v_readfirstlane_b32 s98, v202
	v_readfirstlane_b32 s99, v203
	v_lshlrev_b32_e32 v120, 4, v156
	s_nop 3
	global_load_dwordx4 v[116:119], v120, s[98:99]
	v_and_b32_e32 v255, 7, v156
	v_lshlrev_b32_e32 v255, 5, v255
	v_add_u32_e32 v255, 0x11000, v255
	v_add_u32_e32 v121, 0x11000, v120
	s_waitcnt vmcnt(0)
	ds_write_b128 v121, v[116:119]
	s_waitcnt lgkmcnt(0)
	s_branch .LBB0_761

.LBB0_761:
	v_lshl_add_u64 v[66:67], v[202:203], 0, s[58:59]
	s_barrier
	ds_read_b128 v[116:119], v255 offset:16
	ds_read_b128 v[120:123], v255
	v_add_u32_e32 v255, 0x100, v255
	s_waitcnt vmcnt(7)
	v_lshlrev_b32_e32 v65, 16, v68
	v_lshlrev_b32_e32 v66, 16, v72
	v_sub_f32_e32 v66, v66, v65
	v_and_b32_e32 v67, 0xffff0000, v72
	v_lshlrev_b32_e32 v221, 16, v73
	v_and_b32_e32 v222, 0xffff0000, v73
	v_lshlrev_b32_e32 v224, 16, v70
	v_and_b32_e32 v225, 0xffff0000, v70
	v_lshlrev_b32_e32 v226, 16, v71
	v_and_b32_e32 v227, 0xffff0000, v71
	s_cmpk_eq_i32 s58, 0xf00
	s_waitcnt vmcnt(0) lgkmcnt(0)
	v_fmac_f32_e32 v65, v120, v66
	v_and_b32_e32 v66, 0xffff0000, v68
	v_sub_f32_e32 v67, v67, v66
	v_fmac_f32_e32 v66, v67, v121
	v_lshlrev_b32_e32 v67, 16, v69
	v_sub_f32_e32 v221, v221, v67
	v_fmac_f32_e32 v67, v221, v122
	v_and_b32_e32 v221, 0xffff0000, v69
	v_sub_f32_e32 v222, v222, v221
	v_fmac_f32_e32 v221, v222, v123
	v_lshlrev_b32_e32 v222, 16, v74
	v_sub_f32_e32 v222, v222, v224
	v_fmac_f32_e32 v224, v222, v116
	v_and_b32_e32 v222, 0xffff0000, v74
	v_sub_f32_e32 v222, v222, v225
	v_fmac_f32_e32 v225, v222, v117
	v_lshlrev_b32_e32 v222, 16, v75
	v_sub_f32_e32 v222, v222, v226
	v_fmac_f32_e32 v226, v222, v118
	v_and_b32_e32 v222, 0xffff0000, v75
	v_sub_f32_e32 v222, v222, v227
	v_fmac_f32_e32 v227, v222, v119
	v_cvt_pk_bf16_f32 v222, v65, v66
	v_lshlrev_b32_e32 v65, 16, v80
	v_lshlrev_b32_e32 v66, 16, v84
	v_sub_f32_e32 v66, v66, v65
	v_cvt_pk_bf16_f32 v223, v67, v221
	v_fmac_f32_e32 v65, v66, v120
	v_and_b32_e32 v66, 0xffff0000, v80
	v_and_b32_e32 v67, 0xffff0000, v84
	v_sub_f32_e32 v67, v67, v66
	v_fmac_f32_e32 v66, v67, v121
	v_lshlrev_b32_e32 v67, 16, v81
	v_lshlrev_b32_e32 v221, 16, v85
	v_cvt_pk_bf16_f32 v224, v224, v225
	v_cvt_pk_bf16_f32 v225, v226, v227
	v_sub_f32_e32 v221, v221, v67
	ds_write_b128 v161, v[222:225]
	ds_write_b128 v161, v[76:79] offset:18432
	v_fmac_f32_e32 v67, v221, v122
	v_and_b32_e32 v221, 0xffff0000, v81
	v_and_b32_e32 v222, 0xffff0000, v85
	v_sub_f32_e32 v222, v222, v221
	v_fmac_f32_e32 v221, v222, v123
	v_lshlrev_b32_e32 v224, 16, v82
	v_lshlrev_b32_e32 v222, 16, v86
	v_sub_f32_e32 v222, v222, v224
	v_fmac_f32_e32 v224, v222, v116
	v_and_b32_e32 v225, 0xffff0000, v82
	v_and_b32_e32 v222, 0xffff0000, v86
	v_sub_f32_e32 v222, v222, v225
	v_fmac_f32_e32 v225, v222, v117
	v_lshlrev_b32_e32 v226, 16, v83
	v_lshlrev_b32_e32 v222, 16, v87
	v_sub_f32_e32 v222, v222, v226
	v_fmac_f32_e32 v226, v222, v118
	v_and_b32_e32 v227, 0xffff0000, v83
	v_and_b32_e32 v222, 0xffff0000, v87
	v_sub_f32_e32 v222, v222, v227
	v_fmac_f32_e32 v227, v222, v119
	v_cvt_pk_bf16_f32 v222, v65, v66
	v_lshlrev_b32_e32 v65, 16, v92
	v_lshlrev_b32_e32 v66, 16, v96
	v_sub_f32_e32 v66, v66, v65
	v_cvt_pk_bf16_f32 v223, v67, v221
	v_fmac_f32_e32 v65, v66, v120
	v_and_b32_e32 v66, 0xffff0000, v92
	v_and_b32_e32 v67, 0xffff0000, v96
	v_sub_f32_e32 v67, v67, v66
	v_fmac_f32_e32 v66, v67, v121
	v_lshlrev_b32_e32 v67, 16, v93
	v_lshlrev_b32_e32 v221, 16, v97
	v_cvt_pk_bf16_f32 v224, v224, v225
	v_cvt_pk_bf16_f32 v225, v226, v227
	v_sub_f32_e32 v221, v221, v67
	ds_write_b128 v161, v[222:225] offset:4608
	ds_write_b128 v161, v[88:91] offset:23040
	v_fmac_f32_e32 v67, v221, v122
	v_and_b32_e32 v221, 0xffff0000, v93
	v_and_b32_e32 v222, 0xffff0000, v97
	v_sub_f32_e32 v222, v222, v221
	v_fmac_f32_e32 v221, v222, v123
	v_lshlrev_b32_e32 v224, 16, v94
	v_lshlrev_b32_e32 v222, 16, v98
	v_sub_f32_e32 v222, v222, v224
	v_fmac_f32_e32 v224, v222, v116
	v_and_b32_e32 v225, 0xffff0000, v94
	v_and_b32_e32 v222, 0xffff0000, v98
	v_sub_f32_e32 v222, v222, v225
	v_fmac_f32_e32 v225, v222, v117
	v_lshlrev_b32_e32 v226, 16, v95
	v_lshlrev_b32_e32 v222, 16, v99
	v_sub_f32_e32 v222, v222, v226
	v_fmac_f32_e32 v226, v222, v118
	v_and_b32_e32 v227, 0xffff0000, v95
	v_and_b32_e32 v222, 0xffff0000, v99
	v_sub_f32_e32 v222, v222, v227
	v_fmac_f32_e32 v227, v222, v119
	v_cvt_pk_bf16_f32 v222, v65, v66
	v_lshlrev_b32_e32 v65, 16, v104
	v_lshlrev_b32_e32 v66, 16, v108
	v_sub_f32_e32 v66, v66, v65
	v_cvt_pk_bf16_f32 v223, v67, v221
	v_fmac_f32_e32 v65, v66, v120
	v_and_b32_e32 v66, 0xffff0000, v104
	v_and_b32_e32 v67, 0xffff0000, v108
	v_sub_f32_e32 v67, v67, v66
	v_fmac_f32_e32 v66, v67, v121
	v_lshlrev_b32_e32 v67, 16, v105
	v_lshlrev_b32_e32 v120, 16, v109
	v_sub_f32_e32 v120, v120, v67
	v_fmac_f32_e32 v67, v120, v122
	v_and_b32_e32 v120, 0xffff0000, v105
	v_and_b32_e32 v121, 0xffff0000, v109
	v_sub_f32_e32 v121, v121, v120
	v_fmac_f32_e32 v120, v121, v123
	v_lshlrev_b32_e32 v121, 16, v106
	v_lshlrev_b32_e32 v122, 16, v110
	v_sub_f32_e32 v122, v122, v121
	v_fmac_f32_e32 v121, v122, v116
	v_and_b32_e32 v122, 0xffff0000, v106
	v_and_b32_e32 v116, 0xffff0000, v110
	v_sub_f32_e32 v116, v116, v122
	v_fmac_f32_e32 v122, v116, v117
	v_lshlrev_b32_e32 v123, 16, v107
	v_lshlrev_b32_e32 v116, 16, v111
	v_sub_f32_e32 v116, v116, v123
	v_fmac_f32_e32 v123, v116, v118
	v_and_b32_e32 v221, 0xffff0000, v107
	v_and_b32_e32 v116, 0xffff0000, v111
	v_sub_f32_e32 v116, v116, v221
	v_cvt_pk_bf16_f32 v224, v224, v225
	v_cvt_pk_bf16_f32 v225, v226, v227
	v_fmac_f32_e32 v221, v116, v119
	v_cvt_pk_bf16_f32 v116, v65, v66
	v_cvt_pk_bf16_f32 v117, v67, v120
	v_cvt_pk_bf16_f32 v118, v121, v122
	v_cvt_pk_bf16_f32 v119, v123, v221
	ds_write_b128 v161, v[222:225] offset:9216
	ds_write_b128 v161, v[100:103] offset:27648
	ds_write_b128 v161, v[116:119] offset:13824
	ds_write_b128 v161, v[112:115] offset:32256
	s_waitcnt lgkmcnt(0)
	s_barrier
	s_cbranch_scc1 .LBB0_760
	v_lshl_add_u64 v[66:67], v[142:143], 0, v[186:187]
	global_load_dwordx4 v[68:71], v[66:67], off
	s_and_saveexec_b64 s[60:61], s[16:17]
	s_xor_b64 s[60:61], exec, s[60:61]
	s_cbranch_execz .LBB0_764
	v_lshl_add_u64 v[66:67], v[144:145], 0, v[186:187]
	global_load_dwordx4 v[72:75], v[66:67], off
